# pool groups 3 and 2: trailing-window sums on the matrix cores (transposed LDS reads x 0/1 band), compact register set
# baseline (speedup 1.0000x reference)
.LBB0_124:
	s_cmp_lg_u32 s42, 0x1c0000
	s_cselect_b32 s0, s11, 7
	s_add_i32 s0, s0, s10
	s_lshl_b32 s0, s0, 6
	s_and_b32 s2, s0, 0xfc0
	s_and_b32 s0, s0, 0xfffff000
	s_ashr_i32 s1, s0, 31
	v_add_u32_e32 v84, s2, v144
	s_lshl_b64 s[0:1], s[0:1], 11
	v_ashrrev_i32_e32 v85, 31, v84
	v_lshl_add_u64 v[82:83], v[138:139], 0, s[0:1]
	v_lshlrev_b64 v[84:85], 11, v[84:85]
	s_waitcnt lgkmcnt(0)
	s_barrier
	v_readfirstlane_b32 s66, v157
	v_readfirstlane_b32 s67, v186
	v_and_b32_e32 v248, 15, v186
	v_bfe_u32 v134, v186, 4, 2
	v_bfe_u32 v135, v186, 2, 2
	v_and_b32_e32 v136, 3, v186
	v_lshrrev_b32_e32 v137, 6, v186
	s_lshr_b32 s67, s67, 3
	s_sub_i32 s66, s66, s67
	v_lshl_add_u64 v[84:85], v[82:83], 0, v[84:85]
	global_load_dwordx4 v[102:105], v[84:85], off offset:1536
	v_add_u32_e32 v84, s2, v145
	v_ashrrev_i32_e32 v85, 31, v84
	v_lshlrev_b64 v[84:85], 11, v[84:85]
	v_lshl_add_u64 v[84:85], v[82:83], 0, v[84:85]
	global_load_dwordx4 v[106:109], v[84:85], off offset:1536
	v_add_u32_e32 v84, s2, v146
	v_ashrrev_i32_e32 v85, 31, v84
	v_lshlrev_b64 v[84:85], 11, v[84:85]
	v_lshl_add_u64 v[84:85], v[82:83], 0, v[84:85]
	global_load_dwordx4 v[110:113], v[84:85], off offset:1536
	v_add_u32_e32 v84, s2, v147
	ds_read_b128 v[118:121], v153 offset:33792
	v_ashrrev_i32_e32 v85, 31, v84
	v_lshlrev_b64 v[84:85], 11, v[84:85]
	v_lshl_add_u64 v[82:83], v[82:83], 0, v[84:85]
	v_or_b32_e32 v0, s2, v148
	global_load_dwordx4 v[114:117], v[82:83], off offset:1536
	v_lshl_add_u64 v[82:83], v[140:141], 0, s[0:1]
	v_lshlrev_b32_e32 v0, 11, v0
	v_lshl_add_u64 v[94:95], v[82:83], 0, v[0:1]
	v_add_co_u32_e32 v86, vcc, s97, v94
	s_nop 0
	v_addc_co_u32_e32 v87, vcc, 0, v95, vcc
	v_add_co_u32_e32 v90, vcc, s4, v94
	v_addc_co_u32_e32 v91, vcc, 0, v95, vcc
	global_load_dwordx4 v[82:85], v[94:95], off offset:1536
	v_add_co_u32_e32 v94, vcc, s96, v94
	v_addc_co_u32_e32 v95, vcc, 0, v95, vcc
	global_load_dwordx4 v[86:89], v[86:87], off offset:1536
	global_load_dwordx4 v[90:93], v[90:91], off offset:1536
	global_load_dwordx4 v[94:97], v[94:95], off offset:1536
	v_add_u32_e32 v157, 64, v157
	v_lshl_add_u32 v246, v134, 3, v135
	v_mul_u32_u24_e32 v246, 0x210, v246
	v_lshl_add_u32 v246, v136, 3, v246
	v_lshl_add_u32 v246, v137, 6, v246
	v_add_u32_e32 v247, 16, v248
	v_mul_u32_u24_e32 v247, 0x210, v247
	v_lshl_add_u32 v247, v134, 3, v247
	v_lshl_add_u32 v247, v137, 6, v247
	v_lshlrev_b32_e32 v135, 3, v134
	v_sub_u32_e32 v135, v135, v248
	v_add_u32_e32 v135, -1, v135
	v_mov_b32_e32 v159, 0x3f80
	v_add_u32_e32 v230, 0, v135
	v_and_b32_e32 v230, -16, v230
	v_min_u32_e32 v230, 1, v230
	v_sub_u32_e32 v230, 1, v230
	v_mul_u32_u24_e32 v230, v230, v159
	v_add_u32_e32 v231, 1, v135
	v_and_b32_e32 v231, -16, v231
	v_min_u32_e32 v231, 1, v231
	v_sub_u32_e32 v231, 1, v231
	v_mul_u32_u24_e32 v231, v231, v159
	v_lshl_or_b32 v242, v231, 16, v230
	v_add_u32_e32 v230, 2, v135
	v_and_b32_e32 v230, -16, v230
	v_min_u32_e32 v230, 1, v230
	v_sub_u32_e32 v230, 1, v230
	v_mul_u32_u24_e32 v230, v230, v159
	v_add_u32_e32 v231, 3, v135
	v_and_b32_e32 v231, -16, v231
	v_min_u32_e32 v231, 1, v231
	v_sub_u32_e32 v231, 1, v231
	v_mul_u32_u24_e32 v231, v231, v159
	v_lshl_or_b32 v243, v231, 16, v230
	v_add_u32_e32 v230, 4, v135
	v_and_b32_e32 v230, -16, v230
	v_min_u32_e32 v230, 1, v230
	v_sub_u32_e32 v230, 1, v230
	v_mul_u32_u24_e32 v230, v230, v159
	v_add_u32_e32 v231, 5, v135
	v_and_b32_e32 v231, -16, v231
	v_min_u32_e32 v231, 1, v231
	v_sub_u32_e32 v231, 1, v231
	v_mul_u32_u24_e32 v231, v231, v159
	v_lshl_or_b32 v244, v231, 16, v230
	v_add_u32_e32 v230, 6, v135
	v_and_b32_e32 v230, -16, v230
	v_min_u32_e32 v230, 1, v230
	v_sub_u32_e32 v230, 1, v230
	v_mul_u32_u24_e32 v230, v230, v159
	v_add_u32_e32 v231, 7, v135
	v_and_b32_e32 v231, -16, v231
	v_min_u32_e32 v231, 1, v231
	v_sub_u32_e32 v231, 1, v231
	v_mul_u32_u24_e32 v231, v231, v159
	v_lshl_or_b32 v245, v231, 16, v230
	ds_read_b64_tr_b16 v[160:161], v246 offset:0
	ds_read_b64_tr_b16 v[162:163], v246 offset:2112
	ds_read_b64_tr_b16 v[164:165], v246 offset:8448
	ds_read_b64_tr_b16 v[166:167], v246 offset:10560
	ds_read_b64 v[172:173], v247 offset:0
	ds_read_b64 v[228:229], v247 offset:8448
	s_waitcnt lgkmcnt(2)
	v_mfma_f32_16x16x32_bf16 v[168:171], v[160:163], v[242:245], 0
	v_mfma_f32_16x16x32_bf16 v[238:241], v[164:167], v[242:245], 0
	s_waitcnt lgkmcnt(0)
	v_add_u32_e32 v249, s66, v248
	v_min_i32_e32 v249, 15, v249
	v_add_u32_e32 v249, 1, v249
	v_cvt_f32_i32_e32 v249, v249
	v_rcp_iflag_f32_e32 v249, v249
	v_lshlrev_b32_e32 v134, 16, v172
	v_and_b32_e32 v135, 0xffff0000, v172
	v_lshlrev_b32_e32 v136, 16, v173
	v_and_b32_e32 v137, 0xffff0000, v173
	s_nop 7
	v_fma_f32 v134, v168, v249, -v134
	v_fma_f32 v135, v169, v249, -v135
	v_fma_f32 v136, v170, v249, -v136
	v_fma_f32 v137, v171, v249, -v137
	v_cvt_pk_bf16_f32 v230, v134, v135
	v_cvt_pk_bf16_f32 v231, v136, v137
	s_nop 0
	ds_write_b64 v247, v[230:231] offset:33792
	v_add_u32_e32 v249, s66, v248
	v_add_u32_e32 v249, 16, v249
	v_min_i32_e32 v249, 15, v249
	v_add_u32_e32 v249, 1, v249
	v_cvt_f32_i32_e32 v249, v249
	v_rcp_iflag_f32_e32 v249, v249
	v_lshlrev_b32_e32 v134, 16, v228
	v_and_b32_e32 v135, 0xffff0000, v228
	v_lshlrev_b32_e32 v136, 16, v229
	v_and_b32_e32 v137, 0xffff0000, v229
	v_fma_f32 v134, v238, v249, -v134
	v_fma_f32 v135, v239, v249, -v135
	v_fma_f32 v136, v240, v249, -v136
	v_fma_f32 v137, v241, v249, -v137
	v_cvt_pk_bf16_f32 v230, v134, v135
	v_cvt_pk_bf16_f32 v231, v136, v137
	s_nop 0
	ds_write_b64 v247, v[230:231] offset:42240
	s_waitcnt lgkmcnt(0)
	ds_read_b64_tr_b16 v[160:161], v246 offset:16896
	ds_read_b64_tr_b16 v[162:163], v246 offset:19008
	ds_read_b64_tr_b16 v[164:165], v246 offset:25344
	ds_read_b64_tr_b16 v[166:167], v246 offset:27456
	ds_read_b64 v[172:173], v247 offset:16896
	ds_read_b64 v[228:229], v247 offset:25344
	s_waitcnt lgkmcnt(2)
	v_mfma_f32_16x16x32_bf16 v[168:171], v[160:163], v[242:245], 0
	v_mfma_f32_16x16x32_bf16 v[238:241], v[164:167], v[242:245], 0
	s_waitcnt lgkmcnt(0)
	v_add_u32_e32 v249, s66, v248
	v_add_u32_e32 v249, 32, v249
	v_min_i32_e32 v249, 15, v249
	v_add_u32_e32 v249, 1, v249
	v_cvt_f32_i32_e32 v249, v249
	v_rcp_iflag_f32_e32 v249, v249
	v_lshlrev_b32_e32 v134, 16, v172
	v_and_b32_e32 v135, 0xffff0000, v172
	v_lshlrev_b32_e32 v136, 16, v173
	v_and_b32_e32 v137, 0xffff0000, v173
	s_nop 7
	v_fma_f32 v134, v168, v249, -v134
	v_fma_f32 v135, v169, v249, -v135
	v_fma_f32 v136, v170, v249, -v136
	v_fma_f32 v137, v171, v249, -v137
	v_cvt_pk_bf16_f32 v230, v134, v135
	v_cvt_pk_bf16_f32 v231, v136, v137
	s_nop 0
	ds_write_b64 v247, v[230:231] offset:50688
	v_add_u32_e32 v249, s66, v248
	v_add_u32_e32 v249, 48, v249
	v_min_i32_e32 v249, 15, v249
	v_add_u32_e32 v249, 1, v249
	v_cvt_f32_i32_e32 v249, v249
	v_rcp_iflag_f32_e32 v249, v249
	v_lshlrev_b32_e32 v134, 16, v228
	v_and_b32_e32 v135, 0xffff0000, v228
	v_lshlrev_b32_e32 v136, 16, v229
	v_and_b32_e32 v137, 0xffff0000, v229
	v_fma_f32 v134, v238, v249, -v134
	v_fma_f32 v135, v239, v249, -v135
	v_fma_f32 v136, v240, v249, -v136
	v_fma_f32 v137, v241, v249, -v137
	v_cvt_pk_bf16_f32 v230, v134, v135
	v_cvt_pk_bf16_f32 v231, v136, v137
	s_nop 0
	ds_write_b64 v247, v[230:231] offset:59136
	s_waitcnt lgkmcnt(0)
	ds_read_b64_tr_b16 v[160:161], v246 offset:32
	ds_read_b64_tr_b16 v[162:163], v246 offset:2144
	ds_read_b64_tr_b16 v[164:165], v246 offset:8480
	ds_read_b64_tr_b16 v[166:167], v246 offset:10592
	ds_read_b64 v[172:173], v247 offset:32
	ds_read_b64 v[228:229], v247 offset:8480
	s_waitcnt lgkmcnt(2)
	v_mfma_f32_16x16x32_bf16 v[168:171], v[160:163], v[242:245], 0
	v_mfma_f32_16x16x32_bf16 v[238:241], v[164:167], v[242:245], 0
	s_waitcnt lgkmcnt(0)
	v_add_u32_e32 v249, s66, v248
	v_min_i32_e32 v249, 15, v249
	v_add_u32_e32 v249, 1, v249
	v_cvt_f32_i32_e32 v249, v249
	v_rcp_iflag_f32_e32 v249, v249
	v_lshlrev_b32_e32 v134, 16, v172
	v_and_b32_e32 v135, 0xffff0000, v172
	v_lshlrev_b32_e32 v136, 16, v173
	v_and_b32_e32 v137, 0xffff0000, v173
	s_nop 7
	v_fma_f32 v134, v168, v249, -v134
	v_fma_f32 v135, v169, v249, -v135
	v_fma_f32 v136, v170, v249, -v136
	v_fma_f32 v137, v171, v249, -v137
	v_cvt_pk_bf16_f32 v230, v134, v135
	v_cvt_pk_bf16_f32 v231, v136, v137
	s_nop 0
	ds_write_b64 v247, v[230:231] offset:33824
	v_add_u32_e32 v249, s66, v248
	v_add_u32_e32 v249, 16, v249
	v_min_i32_e32 v249, 15, v249
	v_add_u32_e32 v249, 1, v249
	v_cvt_f32_i32_e32 v249, v249
	v_rcp_iflag_f32_e32 v249, v249
	v_lshlrev_b32_e32 v134, 16, v228
	v_and_b32_e32 v135, 0xffff0000, v228
	v_lshlrev_b32_e32 v136, 16, v229
	v_and_b32_e32 v137, 0xffff0000, v229
	v_fma_f32 v134, v238, v249, -v134
	v_fma_f32 v135, v239, v249, -v135
	v_fma_f32 v136, v240, v249, -v136
	v_fma_f32 v137, v241, v249, -v137
	v_cvt_pk_bf16_f32 v230, v134, v135
	v_cvt_pk_bf16_f32 v231, v136, v137
	s_nop 0
	ds_write_b64 v247, v[230:231] offset:42272
	s_waitcnt lgkmcnt(0)
	ds_read_b64_tr_b16 v[160:161], v246 offset:16928
	ds_read_b64_tr_b16 v[162:163], v246 offset:19040
	ds_read_b64_tr_b16 v[164:165], v246 offset:25376
	ds_read_b64_tr_b16 v[166:167], v246 offset:27488
	ds_read_b64 v[172:173], v247 offset:16928
	ds_read_b64 v[228:229], v247 offset:25376
	s_waitcnt lgkmcnt(2)
	v_mfma_f32_16x16x32_bf16 v[168:171], v[160:163], v[242:245], 0
	v_mfma_f32_16x16x32_bf16 v[238:241], v[164:167], v[242:245], 0
	s_waitcnt lgkmcnt(0)
	v_add_u32_e32 v249, s66, v248
	v_add_u32_e32 v249, 32, v249
	v_min_i32_e32 v249, 15, v249
	v_add_u32_e32 v249, 1, v249
	v_cvt_f32_i32_e32 v249, v249
	v_rcp_iflag_f32_e32 v249, v249
	v_lshlrev_b32_e32 v134, 16, v172
	v_and_b32_e32 v135, 0xffff0000, v172
	v_lshlrev_b32_e32 v136, 16, v173
	v_and_b32_e32 v137, 0xffff0000, v173
	s_nop 7
	v_fma_f32 v134, v168, v249, -v134
	v_fma_f32 v135, v169, v249, -v135
	v_fma_f32 v136, v170, v249, -v136
	v_fma_f32 v137, v171, v249, -v137
	v_cvt_pk_bf16_f32 v230, v134, v135
	v_cvt_pk_bf16_f32 v231, v136, v137
	s_nop 0
	ds_write_b64 v247, v[230:231] offset:50720
	v_add_u32_e32 v249, s66, v248
	v_add_u32_e32 v249, 48, v249
	v_min_i32_e32 v249, 15, v249
	v_add_u32_e32 v249, 1, v249
	v_cvt_f32_i32_e32 v249, v249
	v_rcp_iflag_f32_e32 v249, v249
	v_lshlrev_b32_e32 v134, 16, v228
	v_and_b32_e32 v135, 0xffff0000, v228
	v_lshlrev_b32_e32 v136, 16, v229
	v_and_b32_e32 v137, 0xffff0000, v229
	v_fma_f32 v134, v238, v249, -v134
	v_fma_f32 v135, v239, v249, -v135
	v_fma_f32 v136, v240, v249, -v136
	v_fma_f32 v137, v241, v249, -v137
	v_cvt_pk_bf16_f32 v230, v134, v135
	v_cvt_pk_bf16_f32 v231, v136, v137
	s_nop 0
	ds_write_b64 v247, v[230:231] offset:59168
	s_waitcnt lgkmcnt(0)
	s_barrier
	ds_read_b128 v[134:137], v155 offset:42240
	ds_read_b128 v[164:167], v155 offset:42304
	ds_read_b128 v[238:241], v155 offset:42368
	ds_read_b128 v[242:245], v155 offset:42432
	ds_read_b128 v[246:249], v155 offset:42496
	ds_read_b128 v[228:231], v155 offset:42560
	s_waitcnt lgkmcnt(5)
	v_mfma_f32_16x16x32_bf16 v[160:163], v[2:5], v[134:137], 0
	v_mfma_f32_16x16x32_bf16 v[134:137], v[34:37], v[134:137], 0
	s_waitcnt lgkmcnt(4)
	v_mfma_f32_16x16x32_bf16 v[160:163], v[6:9], v[164:167], v[160:163]
	v_mfma_f32_16x16x32_bf16 v[134:137], v[38:41], v[164:167], v[134:137]
	ds_read_b128 v[164:167], v155 offset:42624
	s_waitcnt lgkmcnt(4)
	v_mfma_f32_16x16x32_bf16 v[160:163], v[10:13], v[238:241], v[160:163]
	v_mfma_f32_16x16x32_bf16 v[134:137], v[42:45], v[238:241], v[134:137]
	ds_read_b128 v[238:241], v155 offset:42688
	s_waitcnt lgkmcnt(4)
	v_mfma_f32_16x16x32_bf16 v[160:163], v[14:17], v[242:245], v[160:163]
	v_mfma_f32_16x16x32_bf16 v[134:137], v[46:49], v[242:245], v[134:137]
	s_waitcnt lgkmcnt(3)
	v_mfma_f32_16x16x32_bf16 v[160:163], v[18:21], v[246:249], v[160:163]
	v_mfma_f32_16x16x32_bf16 v[134:137], v[50:53], v[246:249], v[134:137]
	s_waitcnt lgkmcnt(2)
	v_mfma_f32_16x16x32_bf16 v[160:163], v[22:25], v[228:231], v[160:163]
	v_mfma_f32_16x16x32_bf16 v[134:137], v[54:57], v[228:231], v[134:137]
	s_waitcnt lgkmcnt(1)
	v_mfma_f32_16x16x32_bf16 v[160:163], v[26:29], v[164:167], v[160:163]
	v_mfma_f32_16x16x32_bf16 v[134:137], v[58:61], v[164:167], v[134:137]
	s_waitcnt lgkmcnt(0)
	v_mfma_f32_16x16x32_bf16 v[160:163], v[30:33], v[238:241], v[160:163]
	v_mfma_f32_16x16x32_bf16 v[134:137], v[62:65], v[238:241], v[134:137]
	s_nop 6
	v_add_f32_e32 v163, v73, v163
	v_add_f32_e32 v0, v72, v162
	v_and_b32_e32 v162, 0xffff0000, v131
	v_add_f32_e32 v159, v71, v161
	v_mul_f32_e32 v161, v81, v163
	v_mul_f32_e32 v163, 0xbfb8aa3b, v162
	v_exp_f32_e32 v163, v163
	v_add_f32_e32 v160, v70, v160
	v_mul_f32_e32 v160, v78, v160
	v_mul_f32_e32 v159, v79, v159
	v_add_f32_e32 v163, 1.0, v163
	v_rcp_f32_e32 v163, v163
	v_lshlrev_b32_e32 v131, 16, v131
	v_mul_f32_e32 v0, v80, v0
	v_add_f32_e32 v134, v66, v134
	v_mul_f32_e32 v162, v163, v162
	v_mul_f32_e32 v161, v162, v161
	v_lshlrev_b32_e32 v162, 16, v130
	v_mul_f32_e32 v163, 0xbfb8aa3b, v162
	v_exp_f32_e32 v163, v163
	v_and_b32_e32 v130, 0xffff0000, v130
	v_mul_f32_e32 v134, v74, v134
	v_add_f32_e32 v135, v67, v135
	v_add_f32_e32 v163, 1.0, v163
	v_rcp_f32_e32 v163, v163
	v_mul_f32_e32 v135, v75, v135
	v_add_f32_e32 v136, v68, v136
	v_mul_f32_e32 v136, v76, v136
	v_mul_f32_e32 v162, v163, v162
	v_mul_f32_e32 v160, v162, v160
	v_mul_f32_e32 v162, 0xbfb8aa3b, v130
	v_exp_f32_e32 v162, v162
	s_nop 0
	v_add_f32_e32 v162, 1.0, v162
	v_rcp_f32_e32 v162, v162
	s_nop 0
	v_mul_f32_e32 v130, v162, v130
	v_mul_f32_e32 v130, v130, v159
	v_mul_f32_e32 v159, 0xbfb8aa3b, v131
	v_exp_f32_e32 v159, v159
	v_cvt_pk_bf16_f32 v130, v160, v130
	s_nop 0
	v_add_f32_e32 v159, 1.0, v159
	v_rcp_f32_e32 v159, v159
	s_nop 0
	v_mul_f32_e32 v131, v159, v131
	v_mul_f32_e32 v0, v131, v0
	v_cvt_pk_bf16_f32 v131, v0, v161
	v_add_f32_e32 v0, v69, v137
	v_and_b32_e32 v137, 0xffff0000, v133
	v_mul_f32_e32 v159, 0xbfb8aa3b, v137
	v_exp_f32_e32 v159, v159
	v_mul_f32_e32 v0, v77, v0
	v_lshlrev_b32_e32 v133, 16, v133
	v_add_f32_e32 v159, 1.0, v159
	v_rcp_f32_e32 v159, v159
	s_nop 0
	v_mul_f32_e32 v137, v159, v137
	v_mul_f32_e32 v0, v137, v0
	v_lshlrev_b32_e32 v137, 16, v132
	v_mul_f32_e32 v159, 0xbfb8aa3b, v137
	v_exp_f32_e32 v159, v159
	v_and_b32_e32 v132, 0xffff0000, v132
	v_add_f32_e32 v159, 1.0, v159
	v_rcp_f32_e32 v159, v159
	s_nop 0
	v_mul_f32_e32 v137, v159, v137
	v_mul_f32_e32 v134, v137, v134
	v_mul_f32_e32 v137, 0xbfb8aa3b, v132
	v_exp_f32_e32 v137, v137
	s_nop 0
	v_add_f32_e32 v137, 1.0, v137
	v_rcp_f32_e32 v137, v137
	s_nop 0
	v_mul_f32_e32 v132, v137, v132
	v_mul_f32_e32 v132, v132, v135
	v_mul_f32_e32 v135, 0xbfb8aa3b, v133
	v_exp_f32_e32 v135, v135
	v_cvt_pk_bf16_f32 v132, v134, v132
	s_nop 0
	v_add_f32_e32 v135, 1.0, v135
	v_rcp_f32_e32 v135, v135
	s_nop 0
	v_mul_f32_e32 v133, v135, v133
	v_lshl_add_u64 v[134:135], v[142:143], 0, s[42:43]
	v_mul_f32_e32 v133, v133, v136
	v_add_co_u32_e32 v136, vcc, s9, v134
	v_cvt_pk_bf16_f32 v133, v133, v0
	ds_read_b128 v[164:167], v155 offset:50752
	s_nop 0
	v_addc_co_u32_e32 v137, vcc, 0, v135, vcc
	global_store_dwordx4 v[136:137], v[130:133], off offset:3584
	ds_read_b128 v[130:133], v155 offset:50688
	ds_read_b128 v[238:241], v155 offset:50816
	ds_read_b128 v[242:245], v155 offset:50880
	ds_read_b128 v[246:249], v155 offset:50944
	ds_read_b128 v[228:231], v155 offset:51008
	s_waitcnt lgkmcnt(4)
	v_mfma_f32_16x16x32_bf16 v[160:163], v[2:5], v[130:133], 0
	s_add_u32 s42, s42, 0x40000
	s_addc_u32 s43, s43, 0
	s_add_i32 s11, s11, 1
	v_mfma_f32_16x16x32_bf16 v[130:133], v[34:37], v[130:133], 0
	s_cmp_lg_u32 s42, 0x200000
	s_waitcnt lgkmcnt(5)
	v_mfma_f32_16x16x32_bf16 v[160:163], v[6:9], v[164:167], v[160:163]
	v_mfma_f32_16x16x32_bf16 v[130:133], v[38:41], v[164:167], v[130:133]
	ds_read_b128 v[164:167], v155 offset:51072
	s_waitcnt lgkmcnt(4)
	v_mfma_f32_16x16x32_bf16 v[160:163], v[10:13], v[238:241], v[160:163]
	v_mfma_f32_16x16x32_bf16 v[130:133], v[42:45], v[238:241], v[130:133]
	ds_read_b128 v[238:241], v155 offset:51136
	s_waitcnt lgkmcnt(4)
	v_mfma_f32_16x16x32_bf16 v[160:163], v[14:17], v[242:245], v[160:163]
	v_mfma_f32_16x16x32_bf16 v[130:133], v[46:49], v[242:245], v[130:133]
	s_waitcnt lgkmcnt(3)
	v_mfma_f32_16x16x32_bf16 v[160:163], v[18:21], v[246:249], v[160:163]
	v_mfma_f32_16x16x32_bf16 v[130:133], v[50:53], v[246:249], v[130:133]
	s_waitcnt lgkmcnt(2)
	v_mfma_f32_16x16x32_bf16 v[160:163], v[22:25], v[228:231], v[160:163]
	v_mfma_f32_16x16x32_bf16 v[130:133], v[54:57], v[228:231], v[130:133]
	s_waitcnt lgkmcnt(1)
	v_mfma_f32_16x16x32_bf16 v[160:163], v[26:29], v[164:167], v[160:163]
	v_mfma_f32_16x16x32_bf16 v[130:133], v[58:61], v[164:167], v[130:133]
	s_waitcnt lgkmcnt(0)
	v_mfma_f32_16x16x32_bf16 v[160:163], v[30:33], v[238:241], v[160:163]
	v_mfma_f32_16x16x32_bf16 v[130:133], v[62:65], v[238:241], v[130:133]
	s_nop 6
	v_add_f32_e32 v136, v70, v160
	v_and_b32_e32 v160, 0xffff0000, v127
	v_add_f32_e32 v137, v71, v161
	v_mul_f32_e32 v161, 0xbfb8aa3b, v160
	v_exp_f32_e32 v161, v161
	v_add_f32_e32 v0, v73, v163
	v_mul_f32_e32 v0, v81, v0
	v_mul_f32_e32 v136, v78, v136
	v_add_f32_e32 v161, 1.0, v161
	v_rcp_f32_e32 v161, v161
	v_mul_f32_e32 v137, v79, v137
	v_lshlrev_b32_e32 v127, 16, v127
	v_add_f32_e32 v159, v72, v162
	v_mul_f32_e32 v160, v161, v160
	v_mul_f32_e32 v0, v160, v0
	v_lshlrev_b32_e32 v160, 16, v126
	v_mul_f32_e32 v161, 0xbfb8aa3b, v160
	v_exp_f32_e32 v161, v161
	v_and_b32_e32 v126, 0xffff0000, v126
	v_mul_f32_e32 v159, v80, v159
	v_add_f32_e32 v130, v66, v130
	v_add_f32_e32 v161, 1.0, v161
	v_rcp_f32_e32 v161, v161
	v_mul_f32_e32 v130, v74, v130
	v_add_f32_e32 v131, v67, v131
	v_mul_f32_e32 v131, v75, v131
	v_mul_f32_e32 v160, v161, v160
	v_mul_f32_e32 v136, v160, v136
	v_mul_f32_e32 v160, 0xbfb8aa3b, v126
	v_exp_f32_e32 v160, v160
	v_add_f32_e32 v132, v68, v132
	v_mul_f32_e32 v132, v76, v132
	v_add_f32_e32 v160, 1.0, v160
	v_rcp_f32_e32 v160, v160
	s_nop 0
	v_mul_f32_e32 v126, v160, v126
	v_mul_f32_e32 v126, v126, v137
	v_mul_f32_e32 v137, 0xbfb8aa3b, v127
	v_exp_f32_e32 v137, v137
	v_cvt_pk_bf16_f32 v126, v136, v126
	s_nop 0
	v_add_f32_e32 v137, 1.0, v137
	v_rcp_f32_e32 v137, v137
	s_nop 0
	v_mul_f32_e32 v127, v137, v127
	v_mul_f32_e32 v127, v127, v159
	v_cvt_pk_bf16_f32 v127, v127, v0
	v_add_f32_e32 v0, v69, v133
	v_and_b32_e32 v133, 0xffff0000, v129
	v_mul_f32_e32 v136, 0xbfb8aa3b, v133
	v_exp_f32_e32 v136, v136
	v_mul_f32_e32 v0, v77, v0
	v_lshlrev_b32_e32 v129, 16, v129
	v_add_f32_e32 v136, 1.0, v136
	v_rcp_f32_e32 v136, v136
	s_nop 0
	v_mul_f32_e32 v133, v136, v133
	v_mul_f32_e32 v0, v133, v0
	v_lshlrev_b32_e32 v133, 16, v128
	v_mul_f32_e32 v136, 0xbfb8aa3b, v133
	v_exp_f32_e32 v136, v136
	v_and_b32_e32 v128, 0xffff0000, v128
	v_add_f32_e32 v136, 1.0, v136
	v_rcp_f32_e32 v136, v136
	s_nop 0
	v_mul_f32_e32 v133, v136, v133
	v_mul_f32_e32 v130, v133, v130
	v_mul_f32_e32 v133, 0xbfb8aa3b, v128
	v_exp_f32_e32 v133, v133
	s_nop 0
	v_add_f32_e32 v133, 1.0, v133
	v_rcp_f32_e32 v133, v133
	s_nop 0
	v_mul_f32_e32 v128, v133, v128
	v_mul_f32_e32 v128, v128, v131
	v_mul_f32_e32 v131, 0xbfb8aa3b, v129
	v_exp_f32_e32 v131, v131
	v_cvt_pk_bf16_f32 v128, v130, v128
	v_add_co_u32_e32 v130, vcc, s24, v134
	v_add_f32_e32 v131, 1.0, v131
	v_rcp_f32_e32 v131, v131
	s_nop 0
	v_mul_f32_e32 v129, v131, v129
	v_mul_f32_e32 v129, v129, v132
	v_cvt_pk_bf16_f32 v129, v129, v0
	v_addc_co_u32_e32 v131, vcc, 0, v135, vcc
	global_store_dwordx4 v[130:131], v[126:129], off offset:3584
	ds_read_b128 v[126:129], v155 offset:59136
	ds_read_b128 v[160:163], v155 offset:59200
	ds_read_b128 v[238:241], v155 offset:59264
	ds_read_b128 v[242:245], v155 offset:59328
	ds_read_b128 v[246:249], v155 offset:59392
	ds_read_b128 v[228:231], v155 offset:59456
	s_waitcnt lgkmcnt(5)
	v_mfma_f32_16x16x32_bf16 v[130:133], v[2:5], v[126:129], 0
	v_mfma_f32_16x16x32_bf16 v[126:129], v[34:37], v[126:129], 0
	s_waitcnt lgkmcnt(4)
	v_mfma_f32_16x16x32_bf16 v[130:133], v[6:9], v[160:163], v[130:133]
	v_mfma_f32_16x16x32_bf16 v[126:129], v[38:41], v[160:163], v[126:129]
	ds_read_b128 v[160:163], v155 offset:59520
	s_waitcnt lgkmcnt(4)
	v_mfma_f32_16x16x32_bf16 v[130:133], v[10:13], v[238:241], v[130:133]
	v_mfma_f32_16x16x32_bf16 v[126:129], v[42:45], v[238:241], v[126:129]
	ds_read_b128 v[238:241], v155 offset:59584
	s_waitcnt lgkmcnt(4)
	v_mfma_f32_16x16x32_bf16 v[130:133], v[14:17], v[242:245], v[130:133]
	v_mfma_f32_16x16x32_bf16 v[126:129], v[46:49], v[242:245], v[126:129]
	s_waitcnt lgkmcnt(3)
	v_mfma_f32_16x16x32_bf16 v[130:133], v[18:21], v[246:249], v[130:133]
	v_mfma_f32_16x16x32_bf16 v[126:129], v[50:53], v[246:249], v[126:129]
	s_waitcnt lgkmcnt(2)
	v_mfma_f32_16x16x32_bf16 v[130:133], v[22:25], v[228:231], v[130:133]
	v_mfma_f32_16x16x32_bf16 v[126:129], v[54:57], v[228:231], v[126:129]
	s_waitcnt lgkmcnt(1)
	v_mfma_f32_16x16x32_bf16 v[130:133], v[26:29], v[160:163], v[130:133]
	v_mfma_f32_16x16x32_bf16 v[126:129], v[58:61], v[160:163], v[126:129]
	s_waitcnt lgkmcnt(0)
	v_mfma_f32_16x16x32_bf16 v[130:133], v[30:33], v[238:241], v[130:133]
	v_mfma_f32_16x16x32_bf16 v[126:129], v[62:65], v[238:241], v[126:129]
	s_nop 6
	v_add_f32_e32 v0, v73, v133
	v_and_b32_e32 v133, 0xffff0000, v123
	v_mul_f32_e32 v136, 0xbfb8aa3b, v133
	v_exp_f32_e32 v136, v136
	v_mul_f32_e32 v0, v81, v0
	v_add_f32_e32 v130, v70, v130
	v_mul_f32_e32 v130, v78, v130
	v_add_f32_e32 v136, 1.0, v136
	v_rcp_f32_e32 v136, v136
	v_add_f32_e32 v131, v71, v131
	v_mul_f32_e32 v131, v79, v131
	v_lshlrev_b32_e32 v123, 16, v123
	v_mul_f32_e32 v133, v136, v133
	v_mul_f32_e32 v0, v133, v0
	v_lshlrev_b32_e32 v133, 16, v122
	v_mul_f32_e32 v136, 0xbfb8aa3b, v133
	v_exp_f32_e32 v136, v136
	v_and_b32_e32 v122, 0xffff0000, v122
	v_add_f32_e32 v132, v72, v132
	v_mul_f32_e32 v132, v80, v132
	v_add_f32_e32 v136, 1.0, v136
	v_rcp_f32_e32 v136, v136
	v_add_f32_e32 v126, v66, v126
	v_mul_f32_e32 v126, v74, v126
	v_add_f32_e32 v127, v67, v127
	v_mul_f32_e32 v133, v136, v133
	v_mul_f32_e32 v130, v133, v130
	v_mul_f32_e32 v133, 0xbfb8aa3b, v122
	v_exp_f32_e32 v133, v133
	v_mul_f32_e32 v127, v75, v127
	v_add_f32_e32 v128, v68, v128
	v_mul_f32_e32 v128, v76, v128
	v_add_f32_e32 v133, 1.0, v133
	v_rcp_f32_e32 v133, v133
	s_nop 0
	v_mul_f32_e32 v122, v133, v122
	v_mul_f32_e32 v122, v122, v131
	v_mul_f32_e32 v131, 0xbfb8aa3b, v123
	v_exp_f32_e32 v131, v131
	v_cvt_pk_bf16_f32 v122, v130, v122
	s_nop 0
	v_add_f32_e32 v131, 1.0, v131
	v_rcp_f32_e32 v131, v131
	s_nop 0
	v_mul_f32_e32 v123, v131, v123
	v_mul_f32_e32 v123, v123, v132
	v_cvt_pk_bf16_f32 v123, v123, v0
	v_add_f32_e32 v0, v69, v129
	v_and_b32_e32 v129, 0xffff0000, v125
	v_mul_f32_e32 v130, 0xbfb8aa3b, v129
	v_exp_f32_e32 v130, v130
	v_mul_f32_e32 v0, v77, v0
	v_lshlrev_b32_e32 v125, 16, v125
	v_add_f32_e32 v130, 1.0, v130
	v_rcp_f32_e32 v130, v130
	s_nop 0
	v_mul_f32_e32 v129, v130, v129
	v_mul_f32_e32 v0, v129, v0
	v_lshlrev_b32_e32 v129, 16, v124
	v_mul_f32_e32 v130, 0xbfb8aa3b, v129
	v_exp_f32_e32 v130, v130
	v_and_b32_e32 v124, 0xffff0000, v124
	v_add_f32_e32 v130, 1.0, v130
	v_rcp_f32_e32 v130, v130
	s_nop 0
	v_mul_f32_e32 v129, v130, v129
	v_mul_f32_e32 v126, v129, v126
	v_mul_f32_e32 v129, 0xbfb8aa3b, v124
	v_exp_f32_e32 v129, v129
	s_nop 0
	v_add_f32_e32 v129, 1.0, v129
	v_rcp_f32_e32 v129, v129
	s_nop 0
	v_mul_f32_e32 v124, v129, v124
	v_mul_f32_e32 v124, v124, v127
	v_mul_f32_e32 v127, 0xbfb8aa3b, v125
	v_exp_f32_e32 v127, v127
	v_cvt_pk_bf16_f32 v124, v126, v124
	v_add_co_u32_e32 v126, vcc, s25, v134
	v_add_f32_e32 v127, 1.0, v127
	v_rcp_f32_e32 v127, v127
	s_nop 0
	v_mul_f32_e32 v125, v127, v125
	v_mul_f32_e32 v125, v125, v128
	v_cvt_pk_bf16_f32 v125, v125, v0
	v_addc_co_u32_e32 v127, vcc, 0, v135, vcc
	global_store_dwordx4 v[126:127], v[122:125], off offset:3584
	ds_read_b128 v[122:125], v156 offset:25344
	ds_read_b128 v[130:133], v156 offset:25408
	ds_read_b128 v[238:241], v156 offset:25472
	ds_read_b128 v[242:245], v156 offset:25536
	ds_read_b128 v[246:249], v156 offset:25600
	ds_read_b128 v[228:231], v156 offset:25664
	s_waitcnt lgkmcnt(5)
	v_mfma_f32_16x16x32_bf16 v[126:129], v[2:5], v[122:125], 0
	v_mfma_f32_16x16x32_bf16 v[122:125], v[34:37], v[122:125], 0
	s_waitcnt lgkmcnt(4)
	v_mfma_f32_16x16x32_bf16 v[126:129], v[6:9], v[130:133], v[126:129]
	v_mfma_f32_16x16x32_bf16 v[122:125], v[38:41], v[130:133], v[122:125]
	ds_read_b128 v[130:133], v156 offset:25728
	s_waitcnt lgkmcnt(4)
	v_mfma_f32_16x16x32_bf16 v[126:129], v[10:13], v[238:241], v[126:129]
	v_mfma_f32_16x16x32_bf16 v[122:125], v[42:45], v[238:241], v[122:125]
	ds_read_b128 v[238:241], v156 offset:25792
	s_waitcnt lgkmcnt(4)
	v_mfma_f32_16x16x32_bf16 v[126:129], v[14:17], v[242:245], v[126:129]
	v_mfma_f32_16x16x32_bf16 v[122:125], v[46:49], v[242:245], v[122:125]
	s_waitcnt lgkmcnt(3)
	v_mfma_f32_16x16x32_bf16 v[126:129], v[18:21], v[246:249], v[126:129]
	v_mfma_f32_16x16x32_bf16 v[122:125], v[50:53], v[246:249], v[122:125]
	s_waitcnt lgkmcnt(2)
	v_mfma_f32_16x16x32_bf16 v[126:129], v[22:25], v[228:231], v[126:129]
	v_mfma_f32_16x16x32_bf16 v[122:125], v[54:57], v[228:231], v[122:125]
	s_waitcnt lgkmcnt(1)
	v_mfma_f32_16x16x32_bf16 v[126:129], v[26:29], v[130:133], v[126:129]
	v_mfma_f32_16x16x32_bf16 v[122:125], v[58:61], v[130:133], v[122:125]
	s_waitcnt lgkmcnt(0)
	v_mfma_f32_16x16x32_bf16 v[126:129], v[30:33], v[238:241], v[126:129]
	v_mfma_f32_16x16x32_bf16 v[122:125], v[62:65], v[238:241], v[122:125]
	s_nop 6
	v_add_f32_e32 v0, v73, v129
	v_and_b32_e32 v129, 0xffff0000, v99
	v_mul_f32_e32 v130, 0xbfb8aa3b, v129
	v_exp_f32_e32 v130, v130
	v_mul_f32_e32 v0, v81, v0
	v_add_f32_e32 v126, v70, v126
	v_mul_f32_e32 v126, v78, v126
	v_add_f32_e32 v130, 1.0, v130
	v_rcp_f32_e32 v130, v130
	v_add_f32_e32 v127, v71, v127
	v_mul_f32_e32 v127, v79, v127
	v_lshlrev_b32_e32 v99, 16, v99
	v_mul_f32_e32 v129, v130, v129
	v_mul_f32_e32 v0, v129, v0
	v_lshlrev_b32_e32 v129, 16, v98
	v_mul_f32_e32 v130, 0xbfb8aa3b, v129
	v_exp_f32_e32 v130, v130
	v_and_b32_e32 v98, 0xffff0000, v98
	v_add_f32_e32 v128, v72, v128
	v_mul_f32_e32 v128, v80, v128
	v_add_f32_e32 v130, 1.0, v130
	v_rcp_f32_e32 v130, v130
	v_add_f32_e32 v122, v66, v122
	v_mul_f32_e32 v122, v74, v122
	v_add_f32_e32 v123, v67, v123
	v_mul_f32_e32 v129, v130, v129
	v_mul_f32_e32 v126, v129, v126
	v_mul_f32_e32 v129, 0xbfb8aa3b, v98
	v_exp_f32_e32 v129, v129
	v_mul_f32_e32 v123, v75, v123
	v_add_f32_e32 v124, v68, v124
	v_mul_f32_e32 v124, v76, v124
	v_add_f32_e32 v129, 1.0, v129
	v_rcp_f32_e32 v129, v129
	s_waitcnt vmcnt(6)
	v_mov_b64_e32 v[132:133], v[84:85]
	v_mov_b64_e32 v[130:131], v[82:83]
	v_mul_f32_e32 v98, v129, v98
	v_mul_f32_e32 v98, v98, v127
	v_mul_f32_e32 v127, 0xbfb8aa3b, v99
	v_exp_f32_e32 v127, v127
	v_cvt_pk_bf16_f32 v98, v126, v98
	s_nop 0
	v_add_f32_e32 v127, 1.0, v127
	v_rcp_f32_e32 v127, v127
	s_nop 0
	v_mul_f32_e32 v99, v127, v99
	v_mul_f32_e32 v99, v99, v128
	v_cvt_pk_bf16_f32 v99, v99, v0
	v_add_f32_e32 v0, v69, v125
	v_and_b32_e32 v125, 0xffff0000, v101
	v_mul_f32_e32 v126, 0xbfb8aa3b, v125
	v_exp_f32_e32 v126, v126
	v_mul_f32_e32 v0, v77, v0
	v_lshlrev_b32_e32 v101, 16, v101
	v_add_f32_e32 v126, 1.0, v126
	v_rcp_f32_e32 v126, v126
	s_nop 0
	v_mul_f32_e32 v125, v126, v125
	v_mul_f32_e32 v0, v125, v0
	v_lshlrev_b32_e32 v125, 16, v100
	v_mul_f32_e32 v126, 0xbfb8aa3b, v125
	v_exp_f32_e32 v126, v126
	v_and_b32_e32 v100, 0xffff0000, v100
	v_add_f32_e32 v126, 1.0, v126
	v_rcp_f32_e32 v126, v126
	s_nop 0
	v_mul_f32_e32 v125, v126, v125
	v_mul_f32_e32 v122, v125, v122
	v_mul_f32_e32 v125, 0xbfb8aa3b, v100
	v_exp_f32_e32 v125, v125
	s_waitcnt vmcnt(5)
	v_mov_b64_e32 v[128:129], v[88:89]
	v_mov_b64_e32 v[126:127], v[86:87]
	v_add_f32_e32 v125, 1.0, v125
	v_rcp_f32_e32 v125, v125
	s_nop 0
	v_mul_f32_e32 v100, v125, v100
	v_mul_f32_e32 v100, v100, v123
	v_mul_f32_e32 v123, 0xbfb8aa3b, v101
	v_exp_f32_e32 v123, v123
	v_cvt_pk_bf16_f32 v100, v122, v100
	v_add_co_u32_e32 v122, vcc, s14, v134
	v_add_f32_e32 v123, 1.0, v123
	v_rcp_f32_e32 v123, v123
	s_nop 0
	v_mul_f32_e32 v101, v123, v101
	v_mul_f32_e32 v101, v101, v124
	v_cvt_pk_bf16_f32 v101, v101, v0
	v_addc_co_u32_e32 v123, vcc, 0, v135, vcc
	global_store_dwordx4 v[122:123], v[98:101], off offset:3584
	s_waitcnt vmcnt(5)
	v_mov_b64_e32 v[124:125], v[92:93]
	v_mov_b64_e32 v[122:123], v[90:91]
	s_waitcnt vmcnt(4)
	v_mov_b64_e32 v[100:101], v[96:97]
	v_mov_b64_e32 v[98:99], v[94:95]
	ds_write_b128 v149, v[102:105] offset:8448
	ds_write_b128 v150, v[106:109] offset:8448
	ds_write_b128 v151, v[110:113] offset:8448
	ds_write_b128 v152, v[114:117] offset:8448
	ds_write_b128 v153, v[118:121]
	s_cbranch_scc1 .LBB0_124
	s_waitcnt lgkmcnt(0)
	s_barrier
	s_mov_b64 s[0:1], 0

.LBB0_130:
	s_cmp_lg_u32 s42, 0x1c0000
	s_cselect_b32 s0, s11, 7
	s_add_i32 s0, s0, s10
	s_lshl_b32 s0, s0, 6
	s_and_b32 s2, s0, 0xfc0
	s_and_b32 s0, s0, 0xfffff000
	s_ashr_i32 s1, s0, 31
	v_add_u32_e32 v84, s2, v144
	s_lshl_b64 s[0:1], s[0:1], 11
	v_ashrrev_i32_e32 v85, 31, v84
	v_lshl_add_u64 v[82:83], v[138:139], 0, s[0:1]
	v_lshlrev_b64 v[84:85], 11, v[84:85]
	s_waitcnt lgkmcnt(0)
	s_barrier
	v_readfirstlane_b32 s66, v157
	v_readfirstlane_b32 s67, v186
	v_and_b32_e32 v248, 15, v186
	v_bfe_u32 v134, v186, 4, 2
	v_bfe_u32 v135, v186, 2, 2
	v_and_b32_e32 v136, 3, v186
	v_lshrrev_b32_e32 v137, 6, v186
	s_lshr_b32 s67, s67, 3
	s_sub_i32 s66, s66, s67
	v_lshl_add_u64 v[84:85], v[82:83], 0, v[84:85]
	global_load_dwordx4 v[102:105], v[84:85], off offset:1024
	v_add_u32_e32 v84, s2, v145
	v_ashrrev_i32_e32 v85, 31, v84
	v_lshlrev_b64 v[84:85], 11, v[84:85]
	v_lshl_add_u64 v[84:85], v[82:83], 0, v[84:85]
	global_load_dwordx4 v[106:109], v[84:85], off offset:1024
	v_add_u32_e32 v84, s2, v146
	v_ashrrev_i32_e32 v85, 31, v84
	v_lshlrev_b64 v[84:85], 11, v[84:85]
	v_lshl_add_u64 v[84:85], v[82:83], 0, v[84:85]
	global_load_dwordx4 v[110:113], v[84:85], off offset:1024
	v_add_u32_e32 v84, s2, v147
	ds_read_b128 v[118:121], v153 offset:33792
	v_ashrrev_i32_e32 v85, 31, v84
	v_lshlrev_b64 v[84:85], 11, v[84:85]
	v_lshl_add_u64 v[82:83], v[82:83], 0, v[84:85]
	v_or_b32_e32 v0, s2, v148
	global_load_dwordx4 v[114:117], v[82:83], off offset:1024
	v_lshl_add_u64 v[82:83], v[140:141], 0, s[0:1]
	v_lshlrev_b32_e32 v0, 11, v0
	v_lshl_add_u64 v[94:95], v[82:83], 0, v[0:1]
	v_add_co_u32_e32 v86, vcc, s97, v94
	v_addc_co_u32_e32 v87, vcc, 0, v95, vcc
	v_add_co_u32_e32 v90, vcc, s4, v94
	global_load_dwordx4 v[82:85], v[94:95], off offset:1024
	v_addc_co_u32_e32 v91, vcc, 0, v95, vcc
	v_add_co_u32_e32 v94, vcc, s96, v94
	v_addc_co_u32_e32 v95, vcc, 0, v95, vcc
	global_load_dwordx4 v[86:89], v[86:87], off offset:1024
	global_load_dwordx4 v[90:93], v[90:91], off offset:1024
	global_load_dwordx4 v[94:97], v[94:95], off offset:1024
	v_add_u32_e32 v157, 64, v157
	v_lshl_add_u32 v246, v134, 3, v135
	v_mul_u32_u24_e32 v246, 0x210, v246
	v_lshl_add_u32 v246, v136, 3, v246
	v_lshl_add_u32 v246, v137, 6, v246
	v_add_u32_e32 v247, 16, v248
	v_mul_u32_u24_e32 v247, 0x210, v247
	v_lshl_add_u32 v247, v134, 3, v247
	v_lshl_add_u32 v247, v137, 6, v247
	v_lshlrev_b32_e32 v135, 3, v134
	v_sub_u32_e32 v135, v135, v248
	v_add_u32_e32 v135, -9, v135
	v_mov_b32_e32 v159, 0x3f80
	v_add_u32_e32 v230, 0, v135
	v_and_b32_e32 v230, -8, v230
	v_min_u32_e32 v230, 1, v230
	v_sub_u32_e32 v230, 1, v230
	v_mul_u32_u24_e32 v230, v230, v159
	v_add_u32_e32 v231, 1, v135
	v_and_b32_e32 v231, -8, v231
	v_min_u32_e32 v231, 1, v231
	v_sub_u32_e32 v231, 1, v231
	v_mul_u32_u24_e32 v231, v231, v159
	v_lshl_or_b32 v242, v231, 16, v230
	v_add_u32_e32 v230, 2, v135
	v_and_b32_e32 v230, -8, v230
	v_min_u32_e32 v230, 1, v230
	v_sub_u32_e32 v230, 1, v230
	v_mul_u32_u24_e32 v230, v230, v159
	v_add_u32_e32 v231, 3, v135
	v_and_b32_e32 v231, -8, v231
	v_min_u32_e32 v231, 1, v231
	v_sub_u32_e32 v231, 1, v231
	v_mul_u32_u24_e32 v231, v231, v159
	v_lshl_or_b32 v243, v231, 16, v230
	v_add_u32_e32 v230, 4, v135
	v_and_b32_e32 v230, -8, v230
	v_min_u32_e32 v230, 1, v230
	v_sub_u32_e32 v230, 1, v230
	v_mul_u32_u24_e32 v230, v230, v159
	v_add_u32_e32 v231, 5, v135
	v_and_b32_e32 v231, -8, v231
	v_min_u32_e32 v231, 1, v231
	v_sub_u32_e32 v231, 1, v231
	v_mul_u32_u24_e32 v231, v231, v159
	v_lshl_or_b32 v244, v231, 16, v230
	v_add_u32_e32 v230, 6, v135
	v_and_b32_e32 v230, -8, v230
	v_min_u32_e32 v230, 1, v230
	v_sub_u32_e32 v230, 1, v230
	v_mul_u32_u24_e32 v230, v230, v159
	v_add_u32_e32 v231, 7, v135
	v_and_b32_e32 v231, -8, v231
	v_min_u32_e32 v231, 1, v231
	v_sub_u32_e32 v231, 1, v231
	v_mul_u32_u24_e32 v231, v231, v159
	v_lshl_or_b32 v245, v231, 16, v230
	ds_read_b64_tr_b16 v[160:161], v246 offset:0
	ds_read_b64_tr_b16 v[162:163], v246 offset:2112
	ds_read_b64_tr_b16 v[164:165], v246 offset:8448
	ds_read_b64_tr_b16 v[166:167], v246 offset:10560
	ds_read_b64 v[172:173], v247 offset:0
	ds_read_b64 v[228:229], v247 offset:8448
	s_waitcnt lgkmcnt(2)
	v_mfma_f32_16x16x32_bf16 v[168:171], v[160:163], v[242:245], 0
	v_mfma_f32_16x16x32_bf16 v[238:241], v[164:167], v[242:245], 0
	s_waitcnt lgkmcnt(0)
	v_add_u32_e32 v249, s66, v248
	v_min_i32_e32 v249, 7, v249
	v_add_u32_e32 v249, 1, v249
	v_cvt_f32_i32_e32 v249, v249
	v_rcp_iflag_f32_e32 v249, v249
	v_lshlrev_b32_e32 v134, 16, v172
	v_and_b32_e32 v135, 0xffff0000, v172
	v_lshlrev_b32_e32 v136, 16, v173
	v_and_b32_e32 v137, 0xffff0000, v173
	s_nop 7
	v_fma_f32 v134, v168, v249, -v134
	v_fma_f32 v135, v169, v249, -v135
	v_fma_f32 v136, v170, v249, -v136
	v_fma_f32 v137, v171, v249, -v137
	v_cvt_pk_bf16_f32 v230, v134, v135
	v_cvt_pk_bf16_f32 v231, v136, v137
	s_nop 0
	ds_write_b64 v247, v[230:231] offset:33792
	v_add_u32_e32 v249, s66, v248
	v_add_u32_e32 v249, 16, v249
	v_min_i32_e32 v249, 7, v249
	v_add_u32_e32 v249, 1, v249
	v_cvt_f32_i32_e32 v249, v249
	v_rcp_iflag_f32_e32 v249, v249
	v_lshlrev_b32_e32 v134, 16, v228
	v_and_b32_e32 v135, 0xffff0000, v228
	v_lshlrev_b32_e32 v136, 16, v229
	v_and_b32_e32 v137, 0xffff0000, v229
	v_fma_f32 v134, v238, v249, -v134
	v_fma_f32 v135, v239, v249, -v135
	v_fma_f32 v136, v240, v249, -v136
	v_fma_f32 v137, v241, v249, -v137
	v_cvt_pk_bf16_f32 v230, v134, v135
	v_cvt_pk_bf16_f32 v231, v136, v137
	s_nop 0
	ds_write_b64 v247, v[230:231] offset:42240
	s_waitcnt lgkmcnt(0)
	ds_read_b64_tr_b16 v[160:161], v246 offset:16896
	ds_read_b64_tr_b16 v[162:163], v246 offset:19008
	ds_read_b64_tr_b16 v[164:165], v246 offset:25344
	ds_read_b64_tr_b16 v[166:167], v246 offset:27456
	ds_read_b64 v[172:173], v247 offset:16896
	ds_read_b64 v[228:229], v247 offset:25344
	s_waitcnt lgkmcnt(2)
	v_mfma_f32_16x16x32_bf16 v[168:171], v[160:163], v[242:245], 0
	v_mfma_f32_16x16x32_bf16 v[238:241], v[164:167], v[242:245], 0
	s_waitcnt lgkmcnt(0)
	v_add_u32_e32 v249, s66, v248
	v_add_u32_e32 v249, 32, v249
	v_min_i32_e32 v249, 7, v249
	v_add_u32_e32 v249, 1, v249
	v_cvt_f32_i32_e32 v249, v249
	v_rcp_iflag_f32_e32 v249, v249
	v_lshlrev_b32_e32 v134, 16, v172
	v_and_b32_e32 v135, 0xffff0000, v172
	v_lshlrev_b32_e32 v136, 16, v173
	v_and_b32_e32 v137, 0xffff0000, v173
	s_nop 7
	v_fma_f32 v134, v168, v249, -v134
	v_fma_f32 v135, v169, v249, -v135
	v_fma_f32 v136, v170, v249, -v136
	v_fma_f32 v137, v171, v249, -v137
	v_cvt_pk_bf16_f32 v230, v134, v135
	v_cvt_pk_bf16_f32 v231, v136, v137
	s_nop 0
	ds_write_b64 v247, v[230:231] offset:50688
	v_add_u32_e32 v249, s66, v248
	v_add_u32_e32 v249, 48, v249
	v_min_i32_e32 v249, 7, v249
	v_add_u32_e32 v249, 1, v249
	v_cvt_f32_i32_e32 v249, v249
	v_rcp_iflag_f32_e32 v249, v249
	v_lshlrev_b32_e32 v134, 16, v228
	v_and_b32_e32 v135, 0xffff0000, v228
	v_lshlrev_b32_e32 v136, 16, v229
	v_and_b32_e32 v137, 0xffff0000, v229
	v_fma_f32 v134, v238, v249, -v134
	v_fma_f32 v135, v239, v249, -v135
	v_fma_f32 v136, v240, v249, -v136
	v_fma_f32 v137, v241, v249, -v137
	v_cvt_pk_bf16_f32 v230, v134, v135
	v_cvt_pk_bf16_f32 v231, v136, v137
	s_nop 0
	ds_write_b64 v247, v[230:231] offset:59136
	s_waitcnt lgkmcnt(0)
	ds_read_b64_tr_b16 v[160:161], v246 offset:32
	ds_read_b64_tr_b16 v[162:163], v246 offset:2144
	ds_read_b64_tr_b16 v[164:165], v246 offset:8480
	ds_read_b64_tr_b16 v[166:167], v246 offset:10592
	ds_read_b64 v[172:173], v247 offset:32
	ds_read_b64 v[228:229], v247 offset:8480
	s_waitcnt lgkmcnt(2)
	v_mfma_f32_16x16x32_bf16 v[168:171], v[160:163], v[242:245], 0
	v_mfma_f32_16x16x32_bf16 v[238:241], v[164:167], v[242:245], 0
	s_waitcnt lgkmcnt(0)
	v_add_u32_e32 v249, s66, v248
	v_min_i32_e32 v249, 7, v249
	v_add_u32_e32 v249, 1, v249
	v_cvt_f32_i32_e32 v249, v249
	v_rcp_iflag_f32_e32 v249, v249
	v_lshlrev_b32_e32 v134, 16, v172
	v_and_b32_e32 v135, 0xffff0000, v172
	v_lshlrev_b32_e32 v136, 16, v173
	v_and_b32_e32 v137, 0xffff0000, v173
	s_nop 7
	v_fma_f32 v134, v168, v249, -v134
	v_fma_f32 v135, v169, v249, -v135
	v_fma_f32 v136, v170, v249, -v136
	v_fma_f32 v137, v171, v249, -v137
	v_cvt_pk_bf16_f32 v230, v134, v135
	v_cvt_pk_bf16_f32 v231, v136, v137
	s_nop 0
	ds_write_b64 v247, v[230:231] offset:33824
	v_add_u32_e32 v249, s66, v248
	v_add_u32_e32 v249, 16, v249
	v_min_i32_e32 v249, 7, v249
	v_add_u32_e32 v249, 1, v249
	v_cvt_f32_i32_e32 v249, v249
	v_rcp_iflag_f32_e32 v249, v249
	v_lshlrev_b32_e32 v134, 16, v228
	v_and_b32_e32 v135, 0xffff0000, v228
	v_lshlrev_b32_e32 v136, 16, v229
	v_and_b32_e32 v137, 0xffff0000, v229
	v_fma_f32 v134, v238, v249, -v134
	v_fma_f32 v135, v239, v249, -v135
	v_fma_f32 v136, v240, v249, -v136
	v_fma_f32 v137, v241, v249, -v137
	v_cvt_pk_bf16_f32 v230, v134, v135
	v_cvt_pk_bf16_f32 v231, v136, v137
	s_nop 0
	ds_write_b64 v247, v[230:231] offset:42272
	s_waitcnt lgkmcnt(0)
	ds_read_b64_tr_b16 v[160:161], v246 offset:16928
	ds_read_b64_tr_b16 v[162:163], v246 offset:19040
	ds_read_b64_tr_b16 v[164:165], v246 offset:25376
	ds_read_b64_tr_b16 v[166:167], v246 offset:27488
	ds_read_b64 v[172:173], v247 offset:16928
	ds_read_b64 v[228:229], v247 offset:25376
	s_waitcnt lgkmcnt(2)
	v_mfma_f32_16x16x32_bf16 v[168:171], v[160:163], v[242:245], 0
	v_mfma_f32_16x16x32_bf16 v[238:241], v[164:167], v[242:245], 0
	s_waitcnt lgkmcnt(0)
	v_add_u32_e32 v249, s66, v248
	v_add_u32_e32 v249, 32, v249
	v_min_i32_e32 v249, 7, v249
	v_add_u32_e32 v249, 1, v249
	v_cvt_f32_i32_e32 v249, v249
	v_rcp_iflag_f32_e32 v249, v249
	v_lshlrev_b32_e32 v134, 16, v172
	v_and_b32_e32 v135, 0xffff0000, v172
	v_lshlrev_b32_e32 v136, 16, v173
	v_and_b32_e32 v137, 0xffff0000, v173
	s_nop 7
	v_fma_f32 v134, v168, v249, -v134
	v_fma_f32 v135, v169, v249, -v135
	v_fma_f32 v136, v170, v249, -v136
	v_fma_f32 v137, v171, v249, -v137
	v_cvt_pk_bf16_f32 v230, v134, v135
	v_cvt_pk_bf16_f32 v231, v136, v137
	s_nop 0
	ds_write_b64 v247, v[230:231] offset:50720
	v_add_u32_e32 v249, s66, v248
	v_add_u32_e32 v249, 48, v249
	v_min_i32_e32 v249, 7, v249
	v_add_u32_e32 v249, 1, v249
	v_cvt_f32_i32_e32 v249, v249
	v_rcp_iflag_f32_e32 v249, v249
	v_lshlrev_b32_e32 v134, 16, v228
	v_and_b32_e32 v135, 0xffff0000, v228
	v_lshlrev_b32_e32 v136, 16, v229
	v_and_b32_e32 v137, 0xffff0000, v229
	v_fma_f32 v134, v238, v249, -v134
	v_fma_f32 v135, v239, v249, -v135
	v_fma_f32 v136, v240, v249, -v136
	v_fma_f32 v137, v241, v249, -v137
	v_cvt_pk_bf16_f32 v230, v134, v135
	v_cvt_pk_bf16_f32 v231, v136, v137
	s_nop 0
	ds_write_b64 v247, v[230:231] offset:59168
	s_waitcnt lgkmcnt(0)
	s_barrier
	ds_read_b128 v[134:137], v155 offset:42240
	ds_read_b128 v[164:167], v155 offset:42304
	ds_read_b128 v[238:241], v155 offset:42368
	ds_read_b128 v[242:245], v155 offset:42432
	ds_read_b128 v[246:249], v155 offset:42496
	ds_read_b128 v[228:231], v155 offset:42560
	s_waitcnt lgkmcnt(5)
	v_mfma_f32_16x16x32_bf16 v[160:163], v[2:5], v[134:137], 0
	v_mfma_f32_16x16x32_bf16 v[134:137], v[34:37], v[134:137], 0
	s_waitcnt lgkmcnt(4)
	v_mfma_f32_16x16x32_bf16 v[160:163], v[6:9], v[164:167], v[160:163]
	v_mfma_f32_16x16x32_bf16 v[134:137], v[38:41], v[164:167], v[134:137]
	ds_read_b128 v[164:167], v155 offset:42624
	s_waitcnt lgkmcnt(4)
	v_mfma_f32_16x16x32_bf16 v[160:163], v[10:13], v[238:241], v[160:163]
	v_mfma_f32_16x16x32_bf16 v[134:137], v[42:45], v[238:241], v[134:137]
	ds_read_b128 v[238:241], v155 offset:42688
	s_waitcnt lgkmcnt(4)
	v_mfma_f32_16x16x32_bf16 v[160:163], v[14:17], v[242:245], v[160:163]
	v_mfma_f32_16x16x32_bf16 v[134:137], v[46:49], v[242:245], v[134:137]
	s_waitcnt lgkmcnt(3)
	v_mfma_f32_16x16x32_bf16 v[160:163], v[18:21], v[246:249], v[160:163]
	v_mfma_f32_16x16x32_bf16 v[134:137], v[50:53], v[246:249], v[134:137]
	s_waitcnt lgkmcnt(2)
	v_mfma_f32_16x16x32_bf16 v[160:163], v[22:25], v[228:231], v[160:163]
	v_mfma_f32_16x16x32_bf16 v[134:137], v[54:57], v[228:231], v[134:137]
	s_waitcnt lgkmcnt(1)
	v_mfma_f32_16x16x32_bf16 v[160:163], v[26:29], v[164:167], v[160:163]
	v_mfma_f32_16x16x32_bf16 v[134:137], v[58:61], v[164:167], v[134:137]
	s_waitcnt lgkmcnt(0)
	v_mfma_f32_16x16x32_bf16 v[160:163], v[30:33], v[238:241], v[160:163]
	v_mfma_f32_16x16x32_bf16 v[134:137], v[62:65], v[238:241], v[134:137]
	s_nop 6
	v_add_f32_e32 v159, v70, v160
	v_add_f32_e32 v160, v71, v161
	v_add_f32_e32 v161, v72, v162
	v_and_b32_e32 v162, 0xffff0000, v131
	v_add_f32_e32 v0, v73, v163
	v_mul_f32_e32 v163, 0xbfb8aa3b, v162
	v_exp_f32_e32 v163, v163
	v_mul_f32_e32 v0, v81, v0
	v_mul_f32_e32 v159, v78, v159
	v_mul_f32_e32 v160, v79, v160
	v_add_f32_e32 v163, 1.0, v163
	v_rcp_f32_e32 v163, v163
	v_lshlrev_b32_e32 v131, 16, v131
	v_mul_f32_e32 v161, v80, v161
	v_add_f32_e32 v134, v66, v134
	v_mul_f32_e32 v162, v163, v162
	v_mul_f32_e32 v0, v162, v0
	v_lshlrev_b32_e32 v162, 16, v130
	v_mul_f32_e32 v163, 0xbfb8aa3b, v162
	v_exp_f32_e32 v163, v163
	v_and_b32_e32 v130, 0xffff0000, v130
	v_mul_f32_e32 v134, v74, v134
	v_add_f32_e32 v135, v67, v135
	v_add_f32_e32 v163, 1.0, v163
	v_rcp_f32_e32 v163, v163
	v_mul_f32_e32 v135, v75, v135
	v_add_f32_e32 v136, v68, v136
	v_mul_f32_e32 v136, v76, v136
	v_mul_f32_e32 v162, v163, v162
	v_mul_f32_e32 v159, v162, v159
	v_mul_f32_e32 v162, 0xbfb8aa3b, v130
	v_exp_f32_e32 v162, v162
	s_nop 0
	v_add_f32_e32 v162, 1.0, v162
	v_rcp_f32_e32 v162, v162
	s_nop 0
	v_mul_f32_e32 v130, v162, v130
	v_mul_f32_e32 v130, v130, v160
	v_mul_f32_e32 v160, 0xbfb8aa3b, v131
	v_exp_f32_e32 v160, v160
	v_cvt_pk_bf16_f32 v130, v159, v130
	s_nop 0
	v_add_f32_e32 v160, 1.0, v160
	v_rcp_f32_e32 v160, v160
	s_nop 0
	v_mul_f32_e32 v131, v160, v131
	v_mul_f32_e32 v131, v131, v161
	v_cvt_pk_bf16_f32 v131, v131, v0
	v_add_f32_e32 v0, v69, v137
	v_and_b32_e32 v137, 0xffff0000, v133
	v_mul_f32_e32 v159, 0xbfb8aa3b, v137
	v_exp_f32_e32 v159, v159
	v_mul_f32_e32 v0, v77, v0
	v_lshlrev_b32_e32 v133, 16, v133
	v_add_f32_e32 v159, 1.0, v159
	v_rcp_f32_e32 v159, v159
	s_nop 0
	v_mul_f32_e32 v137, v159, v137
	v_mul_f32_e32 v0, v137, v0
	v_lshlrev_b32_e32 v137, 16, v132
	v_mul_f32_e32 v159, 0xbfb8aa3b, v137
	v_exp_f32_e32 v159, v159
	v_and_b32_e32 v132, 0xffff0000, v132
	v_add_f32_e32 v159, 1.0, v159
	v_rcp_f32_e32 v159, v159
	s_nop 0
	v_mul_f32_e32 v137, v159, v137
	v_mul_f32_e32 v134, v137, v134
	v_mul_f32_e32 v137, 0xbfb8aa3b, v132
	v_exp_f32_e32 v137, v137
	s_nop 0
	v_add_f32_e32 v137, 1.0, v137
	v_rcp_f32_e32 v137, v137
	s_nop 0
	v_mul_f32_e32 v132, v137, v132
	v_mul_f32_e32 v132, v132, v135
	v_mul_f32_e32 v135, 0xbfb8aa3b, v133
	v_exp_f32_e32 v135, v135
	v_cvt_pk_bf16_f32 v132, v134, v132
	s_nop 0
	v_add_f32_e32 v135, 1.0, v135
	v_rcp_f32_e32 v135, v135
	s_nop 0
	v_mul_f32_e32 v133, v135, v133
	v_lshl_add_u64 v[134:135], v[142:143], 0, s[42:43]
	v_mul_f32_e32 v133, v133, v136
	v_add_co_u32_e32 v136, vcc, s9, v134
	v_cvt_pk_bf16_f32 v133, v133, v0
	ds_read_b128 v[164:167], v155 offset:50752
	s_nop 0
	v_addc_co_u32_e32 v137, vcc, 0, v135, vcc
	global_store_dwordx4 v[136:137], v[130:133], off offset:3072
	ds_read_b128 v[130:133], v155 offset:50688
	ds_read_b128 v[238:241], v155 offset:50816
	ds_read_b128 v[242:245], v155 offset:50880
	ds_read_b128 v[246:249], v155 offset:50944
	ds_read_b128 v[228:231], v155 offset:51008
	s_waitcnt lgkmcnt(4)
	v_mfma_f32_16x16x32_bf16 v[160:163], v[2:5], v[130:133], 0
	s_add_u32 s42, s42, 0x40000
	s_addc_u32 s43, s43, 0
	s_add_i32 s11, s11, 1
	v_mfma_f32_16x16x32_bf16 v[130:133], v[34:37], v[130:133], 0
	s_cmp_lg_u32 s42, 0x200000
	s_waitcnt lgkmcnt(5)
	v_mfma_f32_16x16x32_bf16 v[160:163], v[6:9], v[164:167], v[160:163]
	v_mfma_f32_16x16x32_bf16 v[130:133], v[38:41], v[164:167], v[130:133]
	ds_read_b128 v[164:167], v155 offset:51072
	s_waitcnt lgkmcnt(4)
	v_mfma_f32_16x16x32_bf16 v[160:163], v[10:13], v[238:241], v[160:163]
	v_mfma_f32_16x16x32_bf16 v[130:133], v[42:45], v[238:241], v[130:133]
	ds_read_b128 v[238:241], v155 offset:51136
	s_waitcnt lgkmcnt(4)
	v_mfma_f32_16x16x32_bf16 v[160:163], v[14:17], v[242:245], v[160:163]
	v_mfma_f32_16x16x32_bf16 v[130:133], v[46:49], v[242:245], v[130:133]
	s_waitcnt lgkmcnt(3)
	v_mfma_f32_16x16x32_bf16 v[160:163], v[18:21], v[246:249], v[160:163]
	v_mfma_f32_16x16x32_bf16 v[130:133], v[50:53], v[246:249], v[130:133]
	s_waitcnt lgkmcnt(2)
	v_mfma_f32_16x16x32_bf16 v[160:163], v[22:25], v[228:231], v[160:163]
	v_mfma_f32_16x16x32_bf16 v[130:133], v[54:57], v[228:231], v[130:133]
	s_waitcnt lgkmcnt(1)
	v_mfma_f32_16x16x32_bf16 v[160:163], v[26:29], v[164:167], v[160:163]
	v_mfma_f32_16x16x32_bf16 v[130:133], v[58:61], v[164:167], v[130:133]
	s_waitcnt lgkmcnt(0)
	v_mfma_f32_16x16x32_bf16 v[160:163], v[30:33], v[238:241], v[160:163]
	v_mfma_f32_16x16x32_bf16 v[130:133], v[62:65], v[238:241], v[130:133]
	s_nop 6
	v_add_f32_e32 v136, v70, v160
	v_and_b32_e32 v160, 0xffff0000, v127
	v_add_f32_e32 v137, v71, v161
	v_mul_f32_e32 v161, 0xbfb8aa3b, v160
	v_exp_f32_e32 v161, v161
	v_add_f32_e32 v0, v73, v163
	v_mul_f32_e32 v0, v81, v0
	v_mul_f32_e32 v136, v78, v136
	v_add_f32_e32 v161, 1.0, v161
	v_rcp_f32_e32 v161, v161
	v_mul_f32_e32 v137, v79, v137
	v_lshlrev_b32_e32 v127, 16, v127
	v_add_f32_e32 v159, v72, v162
	v_mul_f32_e32 v160, v161, v160
	v_mul_f32_e32 v0, v160, v0
	v_lshlrev_b32_e32 v160, 16, v126
	v_mul_f32_e32 v161, 0xbfb8aa3b, v160
	v_exp_f32_e32 v161, v161
	v_and_b32_e32 v126, 0xffff0000, v126
	v_mul_f32_e32 v159, v80, v159
	v_add_f32_e32 v130, v66, v130
	v_add_f32_e32 v161, 1.0, v161
	v_rcp_f32_e32 v161, v161
	v_mul_f32_e32 v130, v74, v130
	v_add_f32_e32 v131, v67, v131
	v_mul_f32_e32 v131, v75, v131
	v_mul_f32_e32 v160, v161, v160
	v_mul_f32_e32 v136, v160, v136
	v_mul_f32_e32 v160, 0xbfb8aa3b, v126
	v_exp_f32_e32 v160, v160
	v_add_f32_e32 v132, v68, v132
	v_mul_f32_e32 v132, v76, v132
	v_add_f32_e32 v160, 1.0, v160
	v_rcp_f32_e32 v160, v160
	s_nop 0
	v_mul_f32_e32 v126, v160, v126
	v_mul_f32_e32 v126, v126, v137
	v_mul_f32_e32 v137, 0xbfb8aa3b, v127
	v_exp_f32_e32 v137, v137
	v_cvt_pk_bf16_f32 v126, v136, v126
	s_nop 0
	v_add_f32_e32 v137, 1.0, v137
	v_rcp_f32_e32 v137, v137
	s_nop 0
	v_mul_f32_e32 v127, v137, v127
	v_mul_f32_e32 v127, v127, v159
	v_cvt_pk_bf16_f32 v127, v127, v0
	v_add_f32_e32 v0, v69, v133
	v_and_b32_e32 v133, 0xffff0000, v129
	v_mul_f32_e32 v136, 0xbfb8aa3b, v133
	v_exp_f32_e32 v136, v136
	v_mul_f32_e32 v0, v77, v0
	v_lshlrev_b32_e32 v129, 16, v129
	v_add_f32_e32 v136, 1.0, v136
	v_rcp_f32_e32 v136, v136
	s_nop 0
	v_mul_f32_e32 v133, v136, v133
	v_mul_f32_e32 v0, v133, v0
	v_lshlrev_b32_e32 v133, 16, v128
	v_mul_f32_e32 v136, 0xbfb8aa3b, v133
	v_exp_f32_e32 v136, v136
	v_and_b32_e32 v128, 0xffff0000, v128
	v_add_f32_e32 v136, 1.0, v136
	v_rcp_f32_e32 v136, v136
	s_nop 0
	v_mul_f32_e32 v133, v136, v133
	v_mul_f32_e32 v130, v133, v130
	v_mul_f32_e32 v133, 0xbfb8aa3b, v128
	v_exp_f32_e32 v133, v133
	s_nop 0
	v_add_f32_e32 v133, 1.0, v133
	v_rcp_f32_e32 v133, v133
	s_nop 0
	v_mul_f32_e32 v128, v133, v128
	v_mul_f32_e32 v128, v128, v131
	v_mul_f32_e32 v131, 0xbfb8aa3b, v129
	v_exp_f32_e32 v131, v131
	v_cvt_pk_bf16_f32 v128, v130, v128
	v_add_co_u32_e32 v130, vcc, s24, v134
	v_add_f32_e32 v131, 1.0, v131
	v_rcp_f32_e32 v131, v131
	s_nop 0
	v_mul_f32_e32 v129, v131, v129
	v_mul_f32_e32 v129, v129, v132
	v_cvt_pk_bf16_f32 v129, v129, v0
	v_addc_co_u32_e32 v131, vcc, 0, v135, vcc
	global_store_dwordx4 v[130:131], v[126:129], off offset:3072
	ds_read_b128 v[126:129], v155 offset:59136
	ds_read_b128 v[160:163], v155 offset:59200
	ds_read_b128 v[238:241], v155 offset:59264
	ds_read_b128 v[242:245], v155 offset:59328
	ds_read_b128 v[246:249], v155 offset:59392
	ds_read_b128 v[228:231], v155 offset:59456
	s_waitcnt lgkmcnt(5)
	v_mfma_f32_16x16x32_bf16 v[130:133], v[2:5], v[126:129], 0
	v_mfma_f32_16x16x32_bf16 v[126:129], v[34:37], v[126:129], 0
	s_waitcnt lgkmcnt(4)
	v_mfma_f32_16x16x32_bf16 v[130:133], v[6:9], v[160:163], v[130:133]
	v_mfma_f32_16x16x32_bf16 v[126:129], v[38:41], v[160:163], v[126:129]
	ds_read_b128 v[160:163], v155 offset:59520
	s_waitcnt lgkmcnt(4)
	v_mfma_f32_16x16x32_bf16 v[130:133], v[10:13], v[238:241], v[130:133]
	v_mfma_f32_16x16x32_bf16 v[126:129], v[42:45], v[238:241], v[126:129]
	ds_read_b128 v[238:241], v155 offset:59584
	s_waitcnt lgkmcnt(4)
	v_mfma_f32_16x16x32_bf16 v[130:133], v[14:17], v[242:245], v[130:133]
	v_mfma_f32_16x16x32_bf16 v[126:129], v[46:49], v[242:245], v[126:129]
	s_waitcnt lgkmcnt(3)
	v_mfma_f32_16x16x32_bf16 v[130:133], v[18:21], v[246:249], v[130:133]
	v_mfma_f32_16x16x32_bf16 v[126:129], v[50:53], v[246:249], v[126:129]
	s_waitcnt lgkmcnt(2)
	v_mfma_f32_16x16x32_bf16 v[130:133], v[22:25], v[228:231], v[130:133]
	v_mfma_f32_16x16x32_bf16 v[126:129], v[54:57], v[228:231], v[126:129]
	s_waitcnt lgkmcnt(1)
	v_mfma_f32_16x16x32_bf16 v[130:133], v[26:29], v[160:163], v[130:133]
	v_mfma_f32_16x16x32_bf16 v[126:129], v[58:61], v[160:163], v[126:129]
	s_waitcnt lgkmcnt(0)
	v_mfma_f32_16x16x32_bf16 v[130:133], v[30:33], v[238:241], v[130:133]
	v_mfma_f32_16x16x32_bf16 v[126:129], v[62:65], v[238:241], v[126:129]
	s_nop 6
	v_add_f32_e32 v0, v73, v133
	v_and_b32_e32 v133, 0xffff0000, v123
	v_mul_f32_e32 v136, 0xbfb8aa3b, v133
	v_exp_f32_e32 v136, v136
	v_mul_f32_e32 v0, v81, v0
	v_add_f32_e32 v130, v70, v130
	v_mul_f32_e32 v130, v78, v130
	v_add_f32_e32 v136, 1.0, v136
	v_rcp_f32_e32 v136, v136
	v_add_f32_e32 v131, v71, v131
	v_mul_f32_e32 v131, v79, v131
	v_lshlrev_b32_e32 v123, 16, v123
	v_mul_f32_e32 v133, v136, v133
	v_mul_f32_e32 v0, v133, v0
	v_lshlrev_b32_e32 v133, 16, v122
	v_mul_f32_e32 v136, 0xbfb8aa3b, v133
	v_exp_f32_e32 v136, v136
	v_and_b32_e32 v122, 0xffff0000, v122
	v_add_f32_e32 v132, v72, v132
	v_mul_f32_e32 v132, v80, v132
	v_add_f32_e32 v136, 1.0, v136
	v_rcp_f32_e32 v136, v136
	v_add_f32_e32 v126, v66, v126
	v_mul_f32_e32 v126, v74, v126
	v_add_f32_e32 v127, v67, v127
	v_mul_f32_e32 v133, v136, v133
	v_mul_f32_e32 v130, v133, v130
	v_mul_f32_e32 v133, 0xbfb8aa3b, v122
	v_exp_f32_e32 v133, v133
	v_mul_f32_e32 v127, v75, v127
	v_add_f32_e32 v128, v68, v128
	v_mul_f32_e32 v128, v76, v128
	v_add_f32_e32 v133, 1.0, v133
	v_rcp_f32_e32 v133, v133
	s_nop 0
	v_mul_f32_e32 v122, v133, v122
	v_mul_f32_e32 v122, v122, v131
	v_mul_f32_e32 v131, 0xbfb8aa3b, v123
	v_exp_f32_e32 v131, v131
	v_cvt_pk_bf16_f32 v122, v130, v122
	s_nop 0
	v_add_f32_e32 v131, 1.0, v131
	v_rcp_f32_e32 v131, v131
	s_nop 0
	v_mul_f32_e32 v123, v131, v123
	v_mul_f32_e32 v123, v123, v132
	v_cvt_pk_bf16_f32 v123, v123, v0
	v_add_f32_e32 v0, v69, v129
	v_and_b32_e32 v129, 0xffff0000, v125
	v_mul_f32_e32 v130, 0xbfb8aa3b, v129
	v_exp_f32_e32 v130, v130
	v_mul_f32_e32 v0, v77, v0
	v_lshlrev_b32_e32 v125, 16, v125
	v_add_f32_e32 v130, 1.0, v130
	v_rcp_f32_e32 v130, v130
	s_nop 0
	v_mul_f32_e32 v129, v130, v129
	v_mul_f32_e32 v0, v129, v0
	v_lshlrev_b32_e32 v129, 16, v124
	v_mul_f32_e32 v130, 0xbfb8aa3b, v129
	v_exp_f32_e32 v130, v130
	v_and_b32_e32 v124, 0xffff0000, v124
	v_add_f32_e32 v130, 1.0, v130
	v_rcp_f32_e32 v130, v130
	s_nop 0
	v_mul_f32_e32 v129, v130, v129
	v_mul_f32_e32 v126, v129, v126
	v_mul_f32_e32 v129, 0xbfb8aa3b, v124
	v_exp_f32_e32 v129, v129
	s_nop 0
	v_add_f32_e32 v129, 1.0, v129
	v_rcp_f32_e32 v129, v129
	s_nop 0
	v_mul_f32_e32 v124, v129, v124
	v_mul_f32_e32 v124, v124, v127
	v_mul_f32_e32 v127, 0xbfb8aa3b, v125
	v_exp_f32_e32 v127, v127
	v_cvt_pk_bf16_f32 v124, v126, v124
	v_add_co_u32_e32 v126, vcc, s25, v134
	v_add_f32_e32 v127, 1.0, v127
	v_rcp_f32_e32 v127, v127
	s_nop 0
	v_mul_f32_e32 v125, v127, v125
	v_mul_f32_e32 v125, v125, v128
	v_cvt_pk_bf16_f32 v125, v125, v0
	v_addc_co_u32_e32 v127, vcc, 0, v135, vcc
	global_store_dwordx4 v[126:127], v[122:125], off offset:3072
	ds_read_b128 v[122:125], v156 offset:25344
	ds_read_b128 v[130:133], v156 offset:25408
	ds_read_b128 v[238:241], v156 offset:25472
	ds_read_b128 v[242:245], v156 offset:25536
	ds_read_b128 v[246:249], v156 offset:25600
	ds_read_b128 v[228:231], v156 offset:25664
	s_waitcnt lgkmcnt(5)
	v_mfma_f32_16x16x32_bf16 v[126:129], v[2:5], v[122:125], 0
	v_mfma_f32_16x16x32_bf16 v[122:125], v[34:37], v[122:125], 0
	s_waitcnt lgkmcnt(4)
	v_mfma_f32_16x16x32_bf16 v[126:129], v[6:9], v[130:133], v[126:129]
	v_mfma_f32_16x16x32_bf16 v[122:125], v[38:41], v[130:133], v[122:125]
	ds_read_b128 v[130:133], v156 offset:25728
	s_waitcnt lgkmcnt(4)
	v_mfma_f32_16x16x32_bf16 v[126:129], v[10:13], v[238:241], v[126:129]
	v_mfma_f32_16x16x32_bf16 v[122:125], v[42:45], v[238:241], v[122:125]
	ds_read_b128 v[238:241], v156 offset:25792
	s_waitcnt lgkmcnt(4)
	v_mfma_f32_16x16x32_bf16 v[126:129], v[14:17], v[242:245], v[126:129]
	v_mfma_f32_16x16x32_bf16 v[122:125], v[46:49], v[242:245], v[122:125]
	s_waitcnt lgkmcnt(3)
	v_mfma_f32_16x16x32_bf16 v[126:129], v[18:21], v[246:249], v[126:129]
	v_mfma_f32_16x16x32_bf16 v[122:125], v[50:53], v[246:249], v[122:125]
	s_waitcnt lgkmcnt(2)
	v_mfma_f32_16x16x32_bf16 v[126:129], v[22:25], v[228:231], v[126:129]
	v_mfma_f32_16x16x32_bf16 v[122:125], v[54:57], v[228:231], v[122:125]
	s_waitcnt lgkmcnt(1)
	v_mfma_f32_16x16x32_bf16 v[126:129], v[26:29], v[130:133], v[126:129]
	v_mfma_f32_16x16x32_bf16 v[122:125], v[58:61], v[130:133], v[122:125]
	s_waitcnt lgkmcnt(0)
	v_mfma_f32_16x16x32_bf16 v[126:129], v[30:33], v[238:241], v[126:129]
	v_mfma_f32_16x16x32_bf16 v[122:125], v[62:65], v[238:241], v[122:125]
	s_nop 6
	v_add_f32_e32 v0, v73, v129
	v_and_b32_e32 v129, 0xffff0000, v99
	v_mul_f32_e32 v130, 0xbfb8aa3b, v129
	v_exp_f32_e32 v130, v130
	v_mul_f32_e32 v0, v81, v0
	v_add_f32_e32 v126, v70, v126
	v_mul_f32_e32 v126, v78, v126
	v_add_f32_e32 v130, 1.0, v130
	v_rcp_f32_e32 v130, v130
	v_add_f32_e32 v127, v71, v127
	v_mul_f32_e32 v127, v79, v127
	v_lshlrev_b32_e32 v99, 16, v99
	v_mul_f32_e32 v129, v130, v129
	v_mul_f32_e32 v0, v129, v0
	v_lshlrev_b32_e32 v129, 16, v98
	v_mul_f32_e32 v130, 0xbfb8aa3b, v129
	v_exp_f32_e32 v130, v130
	v_and_b32_e32 v98, 0xffff0000, v98
	v_add_f32_e32 v128, v72, v128
	v_mul_f32_e32 v128, v80, v128
	v_add_f32_e32 v130, 1.0, v130
	v_rcp_f32_e32 v130, v130
	v_add_f32_e32 v122, v66, v122
	v_mul_f32_e32 v122, v74, v122
	v_add_f32_e32 v123, v67, v123
	v_mul_f32_e32 v129, v130, v129
	v_mul_f32_e32 v126, v129, v126
	v_mul_f32_e32 v129, 0xbfb8aa3b, v98
	v_exp_f32_e32 v129, v129
	v_mul_f32_e32 v123, v75, v123
	v_add_f32_e32 v124, v68, v124
	v_mul_f32_e32 v124, v76, v124
	v_add_f32_e32 v129, 1.0, v129
	v_rcp_f32_e32 v129, v129
	s_waitcnt vmcnt(6)
	v_mov_b64_e32 v[132:133], v[84:85]
	v_mov_b64_e32 v[130:131], v[82:83]
	v_mul_f32_e32 v98, v129, v98
	v_mul_f32_e32 v98, v98, v127
	v_mul_f32_e32 v127, 0xbfb8aa3b, v99
	v_exp_f32_e32 v127, v127
	v_cvt_pk_bf16_f32 v98, v126, v98
	s_nop 0
	v_add_f32_e32 v127, 1.0, v127
	v_rcp_f32_e32 v127, v127
	s_nop 0
	v_mul_f32_e32 v99, v127, v99
	v_mul_f32_e32 v99, v99, v128
	v_cvt_pk_bf16_f32 v99, v99, v0
	v_add_f32_e32 v0, v69, v125
	v_and_b32_e32 v125, 0xffff0000, v101
	v_mul_f32_e32 v126, 0xbfb8aa3b, v125
	v_exp_f32_e32 v126, v126
	v_mul_f32_e32 v0, v77, v0
	v_lshlrev_b32_e32 v101, 16, v101
	v_add_f32_e32 v126, 1.0, v126
	v_rcp_f32_e32 v126, v126
	s_nop 0
	v_mul_f32_e32 v125, v126, v125
	v_mul_f32_e32 v0, v125, v0
	v_lshlrev_b32_e32 v125, 16, v100
	v_mul_f32_e32 v126, 0xbfb8aa3b, v125
	v_exp_f32_e32 v126, v126
	v_and_b32_e32 v100, 0xffff0000, v100
	v_add_f32_e32 v126, 1.0, v126
	v_rcp_f32_e32 v126, v126
	s_nop 0
	v_mul_f32_e32 v125, v126, v125
	v_mul_f32_e32 v122, v125, v122
	v_mul_f32_e32 v125, 0xbfb8aa3b, v100
	v_exp_f32_e32 v125, v125
	s_waitcnt vmcnt(5)
	v_mov_b64_e32 v[128:129], v[88:89]
	v_mov_b64_e32 v[126:127], v[86:87]
	v_add_f32_e32 v125, 1.0, v125
	v_rcp_f32_e32 v125, v125
	s_nop 0
	v_mul_f32_e32 v100, v125, v100
	v_mul_f32_e32 v100, v100, v123
	v_mul_f32_e32 v123, 0xbfb8aa3b, v101
	v_exp_f32_e32 v123, v123
	v_cvt_pk_bf16_f32 v100, v122, v100
	v_add_co_u32_e32 v122, vcc, s14, v134
	v_add_f32_e32 v123, 1.0, v123
	v_rcp_f32_e32 v123, v123
	s_nop 0
	v_mul_f32_e32 v101, v123, v101
	v_mul_f32_e32 v101, v101, v124
	v_cvt_pk_bf16_f32 v101, v101, v0
	v_addc_co_u32_e32 v123, vcc, 0, v135, vcc
	global_store_dwordx4 v[122:123], v[98:101], off offset:3072
	s_waitcnt vmcnt(5)
	v_mov_b64_e32 v[124:125], v[92:93]
	v_mov_b64_e32 v[122:123], v[90:91]
	s_waitcnt vmcnt(4)
	v_mov_b64_e32 v[100:101], v[96:97]
	v_mov_b64_e32 v[98:99], v[94:95]
	ds_write_b128 v149, v[102:105] offset:8448
	ds_write_b128 v150, v[106:109] offset:8448
	ds_write_b128 v151, v[110:113] offset:8448
	ds_write_b128 v152, v[114:117] offset:8448
	ds_write_b128 v153, v[118:121]
	s_cbranch_scc1 .LBB0_130
	s_waitcnt lgkmcnt(0)
	s_barrier
